# P8 final gate epilogue: 16 gate loads issued up front, counted waits
# speedup vs baseline: 1.0152x; 1.0046x over previous
; __device__ __forceinline__ unsigned cvt_pk_bf16(float lo, float hi) { unsigned r; asm volatile("s_nop 0\n\tv_cvt_pk_bf16_f32 %0, %1, %2" : "=v"(r) : "v"(lo), "v"(hi)); return r; }
;     __device__ __forceinline__ void operator()(AccT& acc, const Unit& u, int wr, int wc, int fr, int fq) const {
;         int row0 = u.pm * 256 + wr * 64 + fr, col0 = u.pn * 256 + wc * 32 + 8 * fq;
;         asm volatile("" : "+v"(row0), "+v"(col0));
; #pragma unroll
;         for (int ai = 0; ai < 2; ++ai)
; #pragma unroll
;             for (int m = 0; m < 4; ++m) { const size_t row = (size_t)(row0 + ai * 128 + m * 16); const bf16_t* gp = proj + row * NP + GATE0 + 3 * DM + col0;
; #pragma unroll
;                 for (int bj = 0; bj < 2; ++bj) { float g8[8], o8[8]; ld8(gp + bj * 128, g8);
; #pragma unroll
;                     for (int e = 0; e < 4; ++e) { o8[e] = acc[ai][bj][m][0][e] * g8[e]; o8[4 + e] = acc[ai][bj][m][1][e] * g8[4 + e]; }
;                     { u32x4 w; w.x = cvt_pk_bf16(o8[0], o8[1]); w.y = cvt_pk_bf16(o8[2], o8[3]); w.z = cvt_pk_bf16(o8[4], o8[5]); w.w = cvt_pk_bf16(o8[6], o8[7]);
;                       __builtin_nontemporal_store(w, (u32x4*)(O + row * DM + col0 + bj * 128)); } }
.LBB0_1370:
	v_mov_b32_e32 v0, v250
	v_mov_b64_e32 v[134:135], s[46:47]
	v_readfirstlane_b32 s6, v0
	s_ashr_i32 s7, s6, 2
	s_andn2_b32 s7, s7, 63
	s_add_i32 s7, s7, s31
	s_lshr_b32 s6, s6, 1
	v_and_or_b32 v132, v0, 15, s7
	s_and_b32 s6, s6, 0x60
	v_lshrrev_b32_e32 v0, 1, v0
	v_and_or_b32 v0, v0, 24, s6
	v_or_b32_e32 v2, s30, v0
	s_mov_b64 s[20:21], 0x7a00
	v_ashrrev_i32_e32 v3, 31, v2
	v_mad_i64_i32 v[136:137], s[6:7], v132, s26, v[134:135]
	v_lshlrev_b64 v[2:3], 1, v[2:3]
	v_lshl_add_u64 v[146:147], v[136:137], 0, v[2:3]
	s_mov_b64 s[20:21], 0x7a00
	v_lshl_add_u64 v[154:155], v[146:147], 0, s[20:21]
	v_ashrrev_i32_e32 v133, 31, v132
	v_lshlrev_b64 v[182:183], 12, v[132:133]
	v_lshl_add_u64 v[182:183], s[48:49], 0, v[182:183]
	v_lshl_add_u64 v[182:183], v[182:183], 0, v[2:3]
	v_readlane_b32 s92, v255, 39
	s_mov_b32 s34, s50
	s_mov_b32 s35, s52
	v_readlane_b32 s93, v255, 40
	s_mov_b32 s91, 0xc2ce8ed0
	global_load_dwordx4 v[132:135], v[154:155], off
	global_load_dwordx4 v[136:139], v[154:155], off offset:256
	s_mov_b64 s[20:21], 0x8a000
	v_lshl_add_u64 v[154:155], v[154:155], 0, s[20:21]
	global_load_dwordx4 v[146:149], v[154:155], off
	global_load_dwordx4 v[150:153], v[154:155], off offset:256
	s_mov_b64 s[20:21], 0x8a000
	v_lshl_add_u64 v[154:155], v[154:155], 0, s[20:21]
	global_load_dwordx4 v[164:167], v[154:155], off
	global_load_dwordx4 v[168:171], v[154:155], off offset:256
	s_mov_b64 s[20:21], 0x8a000
	v_lshl_add_u64 v[154:155], v[154:155], 0, s[20:21]
	global_load_dwordx4 v[172:175], v[154:155], off
	global_load_dwordx4 v[176:179], v[154:155], off offset:256
	s_mov_b64 s[20:21], 0x2b2000
	v_lshl_add_u64 v[154:155], v[154:155], 0, s[20:21]
	global_load_dwordx4 v[188:191], v[154:155], off
	global_load_dwordx4 v[192:195], v[154:155], off offset:256
	s_mov_b64 s[20:21], 0x8a000
	v_lshl_add_u64 v[154:155], v[154:155], 0, s[20:21]
	global_load_dwordx4 v[196:199], v[154:155], off
	global_load_dwordx4 v[200:203], v[154:155], off offset:256
	s_mov_b64 s[20:21], 0x8a000
	v_lshl_add_u64 v[154:155], v[154:155], 0, s[20:21]
	global_load_dwordx4 v[206:209], v[154:155], off
	global_load_dwordx4 v[210:213], v[154:155], off offset:256
	s_mov_b64 s[20:21], 0x8a000
	v_lshl_add_u64 v[154:155], v[154:155], 0, s[20:21]
	global_load_dwordx4 v[214:217], v[154:155], off
	global_load_dwordx4 v[218:221], v[154:155], off offset:256
	s_waitcnt vmcnt(15)
	v_lshlrev_b32_e32 v226, 16, v132
	v_and_b32_e32 v227, 0xffff0000, v132
	v_lshlrev_b32_e32 v228, 16, v133
	v_and_b32_e32 v229, 0xffff0000, v133
	v_lshlrev_b32_e32 v230, 16, v134
	v_and_b32_e32 v231, 0xffff0000, v134
	v_lshlrev_b32_e32 v232, 16, v135
	v_and_b32_e32 v233, 0xffff0000, v135
	v_pk_mul_f32 v[128:129], v[128:129], v[226:227]
	v_pk_mul_f32 v[130:131], v[130:131], v[228:229]
	v_pk_mul_f32 v[124:125], v[124:125], v[230:231]
	v_pk_mul_f32 v[126:127], v[126:127], v[232:233]
	v_cvt_pk_bf16_f32 v132, v128, v129
	v_cvt_pk_bf16_f32 v133, v130, v131
	v_cvt_pk_bf16_f32 v134, v124, v125
	v_cvt_pk_bf16_f32 v135, v126, v127
	global_store_dwordx4 v[182:183], v[132:135], off nt
	s_waitcnt vmcnt(15)
	v_lshlrev_b32_e32 v234, 16, v136
	v_and_b32_e32 v235, 0xffff0000, v136
	v_lshlrev_b32_e32 v236, 16, v137
	v_and_b32_e32 v237, 0xffff0000, v137
	v_lshlrev_b32_e32 v238, 16, v138
	v_and_b32_e32 v239, 0xffff0000, v138
	v_lshlrev_b32_e32 v240, 16, v139
	v_and_b32_e32 v241, 0xffff0000, v139
	v_pk_mul_f32 v[120:121], v[120:121], v[234:235]
	v_pk_mul_f32 v[122:123], v[122:123], v[236:237]
	v_pk_mul_f32 v[116:117], v[116:117], v[238:239]
	v_pk_mul_f32 v[118:119], v[118:119], v[240:241]
	v_cvt_pk_bf16_f32 v136, v120, v121
	v_cvt_pk_bf16_f32 v137, v122, v123
	v_cvt_pk_bf16_f32 v138, v116, v117
	v_cvt_pk_bf16_f32 v139, v118, v119
	global_store_dwordx4 v[182:183], v[136:139], off offset:256 nt
	s_mov_b64 s[20:21], 0x10000
	v_lshl_add_u64 v[182:183], v[182:183], 0, s[20:21]
	s_waitcnt vmcnt(15)
	v_lshlrev_b32_e32 v226, 16, v146
	v_and_b32_e32 v227, 0xffff0000, v146
	v_lshlrev_b32_e32 v228, 16, v147
	v_and_b32_e32 v229, 0xffff0000, v147
	v_lshlrev_b32_e32 v230, 16, v148
	v_and_b32_e32 v231, 0xffff0000, v148
	v_lshlrev_b32_e32 v232, 16, v149
	v_and_b32_e32 v233, 0xffff0000, v149
	v_pk_mul_f32 v[112:113], v[112:113], v[226:227]
	v_pk_mul_f32 v[114:115], v[114:115], v[228:229]
	v_pk_mul_f32 v[108:109], v[108:109], v[230:231]
	v_pk_mul_f32 v[110:111], v[110:111], v[232:233]
	v_cvt_pk_bf16_f32 v146, v112, v113
	v_cvt_pk_bf16_f32 v147, v114, v115
	v_cvt_pk_bf16_f32 v148, v108, v109
	v_cvt_pk_bf16_f32 v149, v110, v111
	global_store_dwordx4 v[182:183], v[146:149], off nt
	s_waitcnt vmcnt(15)
	v_lshlrev_b32_e32 v234, 16, v150
	v_and_b32_e32 v235, 0xffff0000, v150
	v_lshlrev_b32_e32 v236, 16, v151
	v_and_b32_e32 v237, 0xffff0000, v151
	v_lshlrev_b32_e32 v238, 16, v152
	v_and_b32_e32 v239, 0xffff0000, v152
	v_lshlrev_b32_e32 v240, 16, v153
	v_and_b32_e32 v241, 0xffff0000, v153
	v_pk_mul_f32 v[104:105], v[104:105], v[234:235]
	v_pk_mul_f32 v[106:107], v[106:107], v[236:237]
	v_pk_mul_f32 v[100:101], v[100:101], v[238:239]
	v_pk_mul_f32 v[102:103], v[102:103], v[240:241]
	v_cvt_pk_bf16_f32 v150, v104, v105
	v_cvt_pk_bf16_f32 v151, v106, v107
	v_cvt_pk_bf16_f32 v152, v100, v101
	v_cvt_pk_bf16_f32 v153, v102, v103
	global_store_dwordx4 v[182:183], v[150:153], off offset:256 nt
	s_mov_b64 s[20:21], 0x10000
	v_lshl_add_u64 v[182:183], v[182:183], 0, s[20:21]
	s_waitcnt vmcnt(15)
; __device__ __forceinline__ unsigned cvt_pk_bf16(float lo, float hi) { unsigned r; asm volatile("s_nop 0\n\tv_cvt_pk_bf16_f32 %0, %1, %2" : "=v"(r) : "v"(lo), "v"(hi)); return r; }
;     __device__ __forceinline__ void operator()(AccT& acc, const Unit& u, int wr, int wc, int fr, int fq) const {
;     ...
;         for (int ai = 0; ai < 2; ++ai)
; #pragma unroll
;             for (int m = 0; m < 4; ++m) { const size_t row = (size_t)(row0 + ai * 128 + m * 16); const bf16_t* gp = proj + row * NP + GATE0 + 3 * DM + col0;
; #pragma unroll
;                 for (int bj = 0; bj < 2; ++bj) { float g8[8], o8[8]; ld8(gp + bj * 128, g8);
; #pragma unroll
;                     for (int e = 0; e < 4; ++e) { o8[e] = acc[ai][bj][m][0][e] * g8[e]; o8[4 + e] = acc[ai][bj][m][1][e] * g8[4 + e]; }
;                     { u32x4 w; w.x = cvt_pk_bf16(o8[0], o8[1]); w.y = cvt_pk_bf16(o8[2], o8[3]); w.z = cvt_pk_bf16(o8[4], o8[5]); w.w = cvt_pk_bf16(o8[6], o8[7]);
;                       __builtin_nontemporal_store(w, (u32x4*)(O + row * DM + col0 + bj * 128)); } }
	v_lshlrev_b32_e32 v226, 16, v164
	v_and_b32_e32 v227, 0xffff0000, v164
	v_lshlrev_b32_e32 v228, 16, v165
	v_and_b32_e32 v229, 0xffff0000, v165
	v_lshlrev_b32_e32 v230, 16, v166
	v_and_b32_e32 v231, 0xffff0000, v166
	v_lshlrev_b32_e32 v232, 16, v167
	v_and_b32_e32 v233, 0xffff0000, v167
	v_pk_mul_f32 v[96:97], v[96:97], v[226:227]
	v_pk_mul_f32 v[98:99], v[98:99], v[228:229]
	v_pk_mul_f32 v[92:93], v[92:93], v[230:231]
	v_pk_mul_f32 v[94:95], v[94:95], v[232:233]
	v_cvt_pk_bf16_f32 v164, v96, v97
	v_cvt_pk_bf16_f32 v165, v98, v99
	v_cvt_pk_bf16_f32 v166, v92, v93
	v_cvt_pk_bf16_f32 v167, v94, v95
	global_store_dwordx4 v[182:183], v[164:167], off nt
	s_waitcnt vmcnt(15)
	v_lshlrev_b32_e32 v234, 16, v168
	v_and_b32_e32 v235, 0xffff0000, v168
	v_lshlrev_b32_e32 v236, 16, v169
	v_and_b32_e32 v237, 0xffff0000, v169
	v_lshlrev_b32_e32 v238, 16, v170
	v_and_b32_e32 v239, 0xffff0000, v170
	v_lshlrev_b32_e32 v240, 16, v171
	v_and_b32_e32 v241, 0xffff0000, v171
	v_pk_mul_f32 v[88:89], v[88:89], v[234:235]
	v_pk_mul_f32 v[90:91], v[90:91], v[236:237]
	v_pk_mul_f32 v[84:85], v[84:85], v[238:239]
	v_pk_mul_f32 v[86:87], v[86:87], v[240:241]
	v_cvt_pk_bf16_f32 v168, v88, v89
	v_cvt_pk_bf16_f32 v169, v90, v91
	v_cvt_pk_bf16_f32 v170, v84, v85
	v_cvt_pk_bf16_f32 v171, v86, v87
	global_store_dwordx4 v[182:183], v[168:171], off offset:256 nt
	s_mov_b64 s[20:21], 0x10000
	v_lshl_add_u64 v[182:183], v[182:183], 0, s[20:21]
	s_waitcnt vmcnt(15)
	v_lshlrev_b32_e32 v226, 16, v172
	v_and_b32_e32 v227, 0xffff0000, v172
	v_lshlrev_b32_e32 v228, 16, v173
	v_and_b32_e32 v229, 0xffff0000, v173
	v_lshlrev_b32_e32 v230, 16, v174
	v_and_b32_e32 v231, 0xffff0000, v174
	v_lshlrev_b32_e32 v232, 16, v175
	v_and_b32_e32 v233, 0xffff0000, v175
	v_pk_mul_f32 v[80:81], v[80:81], v[226:227]
	v_pk_mul_f32 v[82:83], v[82:83], v[228:229]
	v_pk_mul_f32 v[76:77], v[76:77], v[230:231]
	v_pk_mul_f32 v[78:79], v[78:79], v[232:233]
	v_cvt_pk_bf16_f32 v172, v80, v81
	v_cvt_pk_bf16_f32 v173, v82, v83
	v_cvt_pk_bf16_f32 v174, v76, v77
	v_cvt_pk_bf16_f32 v175, v78, v79
	global_store_dwordx4 v[182:183], v[172:175], off nt
	s_waitcnt vmcnt(15)
	v_lshlrev_b32_e32 v234, 16, v176
	v_and_b32_e32 v235, 0xffff0000, v176
	v_lshlrev_b32_e32 v236, 16, v177
	v_and_b32_e32 v237, 0xffff0000, v177
	v_lshlrev_b32_e32 v238, 16, v178
	v_and_b32_e32 v239, 0xffff0000, v178
	v_lshlrev_b32_e32 v240, 16, v179
	v_and_b32_e32 v241, 0xffff0000, v179
	v_pk_mul_f32 v[72:73], v[72:73], v[234:235]
	v_pk_mul_f32 v[74:75], v[74:75], v[236:237]
	v_pk_mul_f32 v[68:69], v[68:69], v[238:239]
	v_pk_mul_f32 v[70:71], v[70:71], v[240:241]
	v_cvt_pk_bf16_f32 v176, v72, v73
	v_cvt_pk_bf16_f32 v177, v74, v75
	v_cvt_pk_bf16_f32 v178, v68, v69
	v_cvt_pk_bf16_f32 v179, v70, v71
	global_store_dwordx4 v[182:183], v[176:179], off offset:256 nt
	s_mov_b64 s[20:21], 0x50000
	v_lshl_add_u64 v[182:183], v[182:183], 0, s[20:21]
	s_waitcnt vmcnt(15)
	v_lshlrev_b32_e32 v226, 16, v188
	v_and_b32_e32 v227, 0xffff0000, v188
	v_lshlrev_b32_e32 v228, 16, v189
	v_and_b32_e32 v229, 0xffff0000, v189
	v_lshlrev_b32_e32 v230, 16, v190
	v_and_b32_e32 v231, 0xffff0000, v190
	v_lshlrev_b32_e32 v232, 16, v191
	v_and_b32_e32 v233, 0xffff0000, v191
	v_pk_mul_f32 v[64:65], v[64:65], v[226:227]
	v_pk_mul_f32 v[66:67], v[66:67], v[228:229]
	v_pk_mul_f32 v[60:61], v[60:61], v[230:231]
	v_pk_mul_f32 v[62:63], v[62:63], v[232:233]
	v_cvt_pk_bf16_f32 v188, v64, v65
	v_cvt_pk_bf16_f32 v189, v66, v67
	v_cvt_pk_bf16_f32 v190, v60, v61
	v_cvt_pk_bf16_f32 v191, v62, v63
	global_store_dwordx4 v[182:183], v[188:191], off nt
	s_waitcnt vmcnt(15)
	v_lshlrev_b32_e32 v234, 16, v192
	v_and_b32_e32 v235, 0xffff0000, v192
	v_lshlrev_b32_e32 v236, 16, v193
	v_and_b32_e32 v237, 0xffff0000, v193
	v_lshlrev_b32_e32 v238, 16, v194
	v_and_b32_e32 v239, 0xffff0000, v194
	v_lshlrev_b32_e32 v240, 16, v195
	v_and_b32_e32 v241, 0xffff0000, v195
	v_pk_mul_f32 v[56:57], v[56:57], v[234:235]
	v_pk_mul_f32 v[58:59], v[58:59], v[236:237]
	v_pk_mul_f32 v[52:53], v[52:53], v[238:239]
	v_pk_mul_f32 v[54:55], v[54:55], v[240:241]
	v_cvt_pk_bf16_f32 v192, v56, v57
	v_cvt_pk_bf16_f32 v193, v58, v59
	v_cvt_pk_bf16_f32 v194, v52, v53
	v_cvt_pk_bf16_f32 v195, v54, v55
	global_store_dwordx4 v[182:183], v[192:195], off offset:256 nt
	s_mov_b64 s[20:21], 0x10000
	v_lshl_add_u64 v[182:183], v[182:183], 0, s[20:21]
	s_waitcnt vmcnt(15)
; __device__ __forceinline__ unsigned cvt_pk_bf16(float lo, float hi) { unsigned r; asm volatile("s_nop 0\n\tv_cvt_pk_bf16_f32 %0, %1, %2" : "=v"(r) : "v"(lo), "v"(hi)); return r; }
;     __device__ __forceinline__ void operator()(AccT& acc, const Unit& u, int wr, int wc, int fr, int fq) const {
;     ...
;         for (int ai = 0; ai < 2; ++ai)
; #pragma unroll
;             for (int m = 0; m < 4; ++m) { const size_t row = (size_t)(row0 + ai * 128 + m * 16); const bf16_t* gp = proj + row * NP + GATE0 + 3 * DM + col0;
; #pragma unroll
;                 for (int bj = 0; bj < 2; ++bj) { float g8[8], o8[8]; ld8(gp + bj * 128, g8);
; #pragma unroll
;                     for (int e = 0; e < 4; ++e) { o8[e] = acc[ai][bj][m][0][e] * g8[e]; o8[4 + e] = acc[ai][bj][m][1][e] * g8[4 + e]; }
;                     { u32x4 w; w.x = cvt_pk_bf16(o8[0], o8[1]); w.y = cvt_pk_bf16(o8[2], o8[3]); w.z = cvt_pk_bf16(o8[4], o8[5]); w.w = cvt_pk_bf16(o8[6], o8[7]);
;                       __builtin_nontemporal_store(w, (u32x4*)(O + row * DM + col0 + bj * 128)); } }
	v_lshlrev_b32_e32 v226, 16, v196
	v_and_b32_e32 v227, 0xffff0000, v196
	v_lshlrev_b32_e32 v228, 16, v197
	v_and_b32_e32 v229, 0xffff0000, v197
	v_lshlrev_b32_e32 v230, 16, v198
	v_and_b32_e32 v231, 0xffff0000, v198
	v_lshlrev_b32_e32 v232, 16, v199
	v_and_b32_e32 v233, 0xffff0000, v199
	v_pk_mul_f32 v[48:49], v[48:49], v[226:227]
	v_pk_mul_f32 v[50:51], v[50:51], v[228:229]
	v_pk_mul_f32 v[44:45], v[44:45], v[230:231]
	v_pk_mul_f32 v[46:47], v[46:47], v[232:233]
	v_cvt_pk_bf16_f32 v196, v48, v49
	v_cvt_pk_bf16_f32 v197, v50, v51
	v_cvt_pk_bf16_f32 v198, v44, v45
	v_cvt_pk_bf16_f32 v199, v46, v47
	global_store_dwordx4 v[182:183], v[196:199], off nt
	s_waitcnt vmcnt(15)
	v_lshlrev_b32_e32 v234, 16, v200
	v_and_b32_e32 v235, 0xffff0000, v200
	v_lshlrev_b32_e32 v236, 16, v201
	v_and_b32_e32 v237, 0xffff0000, v201
	v_lshlrev_b32_e32 v238, 16, v202
	v_and_b32_e32 v239, 0xffff0000, v202
	v_lshlrev_b32_e32 v240, 16, v203
	v_and_b32_e32 v241, 0xffff0000, v203
	v_pk_mul_f32 v[40:41], v[40:41], v[234:235]
	v_pk_mul_f32 v[42:43], v[42:43], v[236:237]
	v_pk_mul_f32 v[36:37], v[36:37], v[238:239]
	v_pk_mul_f32 v[38:39], v[38:39], v[240:241]
	v_cvt_pk_bf16_f32 v200, v40, v41
	v_cvt_pk_bf16_f32 v201, v42, v43
	v_cvt_pk_bf16_f32 v202, v36, v37
	v_cvt_pk_bf16_f32 v203, v38, v39
	global_store_dwordx4 v[182:183], v[200:203], off offset:256 nt
	s_mov_b64 s[20:21], 0x10000
	v_lshl_add_u64 v[182:183], v[182:183], 0, s[20:21]
	s_waitcnt vmcnt(15)
	v_lshlrev_b32_e32 v226, 16, v206
	v_and_b32_e32 v227, 0xffff0000, v206
	v_lshlrev_b32_e32 v228, 16, v207
	v_and_b32_e32 v229, 0xffff0000, v207
	v_lshlrev_b32_e32 v230, 16, v208
	v_and_b32_e32 v231, 0xffff0000, v208
	v_lshlrev_b32_e32 v232, 16, v209
	v_and_b32_e32 v233, 0xffff0000, v209
	v_pk_mul_f32 v[32:33], v[32:33], v[226:227]
	v_pk_mul_f32 v[34:35], v[34:35], v[228:229]
	v_pk_mul_f32 v[28:29], v[28:29], v[230:231]
	v_pk_mul_f32 v[30:31], v[30:31], v[232:233]
	v_cvt_pk_bf16_f32 v206, v32, v33
	v_cvt_pk_bf16_f32 v207, v34, v35
	v_cvt_pk_bf16_f32 v208, v28, v29
	v_cvt_pk_bf16_f32 v209, v30, v31
	global_store_dwordx4 v[182:183], v[206:209], off nt
	s_waitcnt vmcnt(15)
	v_lshlrev_b32_e32 v234, 16, v210
	v_and_b32_e32 v235, 0xffff0000, v210
	v_lshlrev_b32_e32 v236, 16, v211
	v_and_b32_e32 v237, 0xffff0000, v211
	v_lshlrev_b32_e32 v238, 16, v212
	v_and_b32_e32 v239, 0xffff0000, v212
	v_lshlrev_b32_e32 v240, 16, v213
	v_and_b32_e32 v241, 0xffff0000, v213
	v_pk_mul_f32 v[24:25], v[24:25], v[234:235]
	v_pk_mul_f32 v[26:27], v[26:27], v[236:237]
	v_pk_mul_f32 v[20:21], v[20:21], v[238:239]
	v_pk_mul_f32 v[22:23], v[22:23], v[240:241]
	v_cvt_pk_bf16_f32 v210, v24, v25
	v_cvt_pk_bf16_f32 v211, v26, v27
	v_cvt_pk_bf16_f32 v212, v20, v21
	v_cvt_pk_bf16_f32 v213, v22, v23
	global_store_dwordx4 v[182:183], v[210:213], off offset:256 nt
	s_mov_b64 s[20:21], 0x10000
	v_lshl_add_u64 v[182:183], v[182:183], 0, s[20:21]
	s_waitcnt vmcnt(15)
	v_lshlrev_b32_e32 v226, 16, v214
	v_and_b32_e32 v227, 0xffff0000, v214
	v_lshlrev_b32_e32 v228, 16, v215
	v_and_b32_e32 v229, 0xffff0000, v215
	v_lshlrev_b32_e32 v230, 16, v216
	v_and_b32_e32 v231, 0xffff0000, v216
	v_lshlrev_b32_e32 v232, 16, v217
	v_and_b32_e32 v233, 0xffff0000, v217
	v_pk_mul_f32 v[16:17], v[16:17], v[226:227]
	v_pk_mul_f32 v[18:19], v[18:19], v[228:229]
	v_pk_mul_f32 v[12:13], v[12:13], v[230:231]
	v_pk_mul_f32 v[14:15], v[14:15], v[232:233]
	v_cvt_pk_bf16_f32 v214, v16, v17
	v_cvt_pk_bf16_f32 v215, v18, v19
	v_cvt_pk_bf16_f32 v216, v12, v13
	v_cvt_pk_bf16_f32 v217, v14, v15
	global_store_dwordx4 v[182:183], v[214:217], off nt
	s_waitcnt vmcnt(15)
	v_lshlrev_b32_e32 v234, 16, v218
	v_and_b32_e32 v235, 0xffff0000, v218
	v_lshlrev_b32_e32 v236, 16, v219
	v_and_b32_e32 v237, 0xffff0000, v219
	v_lshlrev_b32_e32 v238, 16, v220
	v_and_b32_e32 v239, 0xffff0000, v220
	v_lshlrev_b32_e32 v240, 16, v221
	v_and_b32_e32 v241, 0xffff0000, v221
	v_pk_mul_f32 v[8:9], v[8:9], v[234:235]
	v_pk_mul_f32 v[10:11], v[10:11], v[236:237]
	v_pk_mul_f32 v[4:5], v[4:5], v[238:239]
	v_pk_mul_f32 v[6:7], v[6:7], v[240:241]
	v_cvt_pk_bf16_f32 v218, v8, v9
	v_cvt_pk_bf16_f32 v219, v10, v11
	v_cvt_pk_bf16_f32 v220, v4, v5
	v_cvt_pk_bf16_f32 v221, v6, v7
	global_store_dwordx4 v[182:183], v[218:221], off offset:256 nt
	s_and_b64 vcc, exec, s[44:45]
	s_mov_b64 s[6:7], s[62:63]
	s_mov_b64 s[20:21], s[54:55]
	s_cbranch_vccnz .LBB0_1381
